# P2 row loop: wave-wide sums of squares by DPP adds and permlane swaps instead of ~10 dependent ds_bpermute round trips per row
# speedup vs baseline: 1.0320x; 1.0031x over previous
.LBB0_487:
	s_mov_b64 s[10:11], -1
	s_cmp_gt_i32 s4, 0x83ff
	v_mbcnt_hi_u32_b32 v122, -1, v1
	s_cbranch_scc0 .LBB0_489
	s_add_i32 s14, s4, 0xffff7c00
	s_lshl_b64 s[10:11], s[14:15], 12
	v_lshl_add_u64 v[74:75], v[116:117], 0, s[10:11]
	global_load_dwordx4 v[78:81], v[74:75], off offset:16
	global_load_dwordx4 v[82:85], v[74:75], off
	s_waitcnt lgkmcnt(0)
	global_load_dwordx4 v[70:73], v[74:75], off offset:2064
	s_nop 0
	global_load_dwordx4 v[74:77], v[74:75], off offset:2048
	s_lshl_b64 s[10:11], s[14:15], 11
	s_lshl_b64 s[12:13], s[14:15], 10
	s_waitcnt vmcnt(3)
	v_pk_mul_f32 v[124:125], v[78:79], v[78:79]
	s_waitcnt vmcnt(2)
	v_mul_f32_e32 v88, v83, v83
	v_fmac_f32_e32 v88, v82, v82
	v_pk_mul_f32 v[120:121], v[84:85], v[84:85]
	s_nop 0
	v_add_f32_e32 v88, v120, v88
	v_add_f32_e32 v88, v121, v88
	v_add_f32_e32 v88, v124, v88
	v_add_f32_e32 v88, v125, v88
	v_pk_mul_f32 v[120:121], v[80:81], v[80:81]
	s_nop 0
	v_add_f32_e32 v88, v120, v88
	v_add_f32_e32 v88, v121, v88
	s_nop 1
	v_add_f32_dpp v88, v88, v88 quad_perm:[1,0,3,2] row_mask:0xf bank_mask:0xf
	s_nop 1
	v_add_f32_dpp v88, v88, v88 quad_perm:[2,3,0,1] row_mask:0xf bank_mask:0xf
	s_nop 1
	v_add_f32_dpp v88, v88, v88 row_half_mirror row_mask:0xf bank_mask:0xf
	s_nop 1
	v_add_f32_dpp v88, v88, v88 row_mirror row_mask:0xf bank_mask:0xf
	v_fmamk_f32 v88, v88, 0x3c000000, v118
	v_cmp_gt_f32_e32 vcc, s17, v88
	v_mul_f32_e32 v120, 0x4b800000, v88
	s_nop 0
	v_cndmask_b32_e32 v88, v88, v120, vcc
	v_rsq_f32_e32 v88, v88
	s_nop 0
	v_mul_f32_e32 v120, 0x45800000, v88
	v_cndmask_b32_e32 v88, v88, v120, vcc
	v_pk_mul_f32 v[82:83], v[82:83], v[88:89] op_sel_hi:[1,0]
	v_pk_mul_f32 v[84:85], v[84:85], v[88:89] op_sel_hi:[1,0]
	v_pk_mul_f32 v[78:79], v[78:79], v[88:89] op_sel_hi:[1,0]
	v_pk_mul_f32 v[80:81], v[80:81], v[88:89] op_sel_hi:[1,0]
	v_lshl_add_u64 v[120:121], v[92:93], 0, s[10:11]
	v_pk_mul_f32 v[78:79], v[158:159], v[78:79]
	v_pk_mul_f32 v[82:83], v[154:155], v[82:83]
	v_pk_mul_f32 v[84:85], v[156:157], v[84:85]
	v_pk_mul_f32 v[80:81], v[160:161], v[80:81]
	global_store_dwordx4 v[120:121], v[82:85], off
	global_store_dwordx4 v[120:121], v[78:81], off offset:16
	s_nop 0
	v_cvt_pk_bf16_f32 v82, v82, v83
	v_cvt_pk_bf16_f32 v83, v84, v85
	v_cvt_pk_bf16_f32 v84, v78, v79
	v_cvt_pk_bf16_f32 v85, v80, v81
	v_lshl_add_u64 v[78:79], v[94:95], 0, s[12:13]
	global_store_dwordx4 v[78:79], v[82:85], off
	v_lshl_add_u64 v[78:79], v[96:97], 0, s[10:11]
	s_waitcnt vmcnt(3)
	global_store_dwordx4 v[78:79], v[74:77], off
	global_store_dwordx4 v[78:79], v[70:73], off offset:16
	s_nop 0
	v_cvt_pk_bf16_f32 v74, v74, v75
	v_cvt_pk_bf16_f32 v75, v76, v77
	v_cvt_pk_bf16_f32 v76, v70, v71
	v_cvt_pk_bf16_f32 v77, v72, v73
	v_lshl_add_u64 v[70:71], v[98:99], 0, s[12:13]
	global_store_dwordx4 v[70:71], v[74:77], off
	s_cbranch_execnz .LBB0_486
	s_branch .LBB0_490

.LBB0_496:
	s_or_b64 exec, exec, s[22:23]
	s_waitcnt vmcnt(1)
	v_lshlrev_b32_e32 v120, 16, v82
	v_pk_fma_f32 v[124:125], v[64:65], v[120:121], v[68:69] op_sel_hi:[1,0,1]
	v_pk_fma_f32 v[120:121], v[62:63], v[120:121], v[66:67] op_sel_hi:[1,0,1]
	s_waitcnt vmcnt(0)
	v_lshlrev_b32_e32 v126, 16, v78
	v_pk_fma_f32 v[124:125], v[32:33], v[126:127], v[124:125] op_sel_hi:[1,0,1]
	v_pk_fma_f32 v[120:121], v[30:31], v[126:127], v[120:121] op_sel_hi:[1,0,1]
	v_bfi_b32 v82, v91, 0, v82
	v_pk_fma_f32 v[124:125], v[4:5], v[82:83], v[124:125] op_sel_hi:[1,0,1]
	v_pk_fma_f32 v[120:121], v[2:3], v[82:83], v[120:121] op_sel_hi:[1,0,1]
	v_bfi_b32 v78, v91, 0, v78
	v_pk_fma_f32 v[124:125], v[36:37], v[78:79], v[124:125] op_sel_hi:[1,0,1]
	v_pk_fma_f32 v[120:121], v[34:35], v[78:79], v[120:121] op_sel_hi:[1,0,1]
	v_lshlrev_b32_e32 v78, 16, v83
	v_pk_fma_f32 v[124:125], v[8:9], v[78:79], v[124:125] op_sel_hi:[1,0,1]
	v_pk_fma_f32 v[120:121], v[6:7], v[78:79], v[120:121] op_sel_hi:[1,0,1]
	v_lshlrev_b32_e32 v78, 16, v79
	v_pk_fma_f32 v[124:125], v[40:41], v[78:79], v[124:125] op_sel_hi:[1,0,1]
	v_pk_fma_f32 v[120:121], v[38:39], v[78:79], v[120:121] op_sel_hi:[1,0,1]
	v_bfi_b32 v78, v91, 0, v83
	v_pk_fma_f32 v[82:83], v[12:13], v[78:79], v[124:125] op_sel_hi:[1,0,1]
	v_pk_fma_f32 v[120:121], v[10:11], v[78:79], v[120:121] op_sel_hi:[1,0,1]
	v_bfi_b32 v78, v91, 0, v79
	v_pk_fma_f32 v[82:83], v[44:45], v[78:79], v[82:83] op_sel_hi:[1,0,1]
	v_pk_fma_f32 v[78:79], v[42:43], v[78:79], v[120:121] op_sel_hi:[1,0,1]
	v_lshlrev_b32_e32 v120, 16, v84
	v_pk_fma_f32 v[82:83], v[16:17], v[120:121], v[82:83] op_sel_hi:[1,0,1]
	v_pk_fma_f32 v[78:79], v[14:15], v[120:121], v[78:79] op_sel_hi:[1,0,1]
	v_lshlrev_b32_e32 v120, 16, v80
	v_pk_fma_f32 v[82:83], v[48:49], v[120:121], v[82:83] op_sel_hi:[1,0,1]
	v_pk_fma_f32 v[78:79], v[46:47], v[120:121], v[78:79] op_sel_hi:[1,0,1]
	v_bfi_b32 v84, v91, 0, v84
	v_pk_fma_f32 v[82:83], v[20:21], v[84:85], v[82:83] op_sel_hi:[1,0,1]
	v_pk_fma_f32 v[78:79], v[18:19], v[84:85], v[78:79] op_sel_hi:[1,0,1]
	v_bfi_b32 v80, v91, 0, v80
	v_pk_fma_f32 v[82:83], v[52:53], v[80:81], v[82:83] op_sel_hi:[1,0,1]
	v_pk_fma_f32 v[78:79], v[50:51], v[80:81], v[78:79] op_sel_hi:[1,0,1]
	v_lshlrev_b32_e32 v80, 16, v85
	v_pk_fma_f32 v[82:83], v[24:25], v[80:81], v[82:83] op_sel_hi:[1,0,1]
	v_pk_fma_f32 v[78:79], v[22:23], v[80:81], v[78:79] op_sel_hi:[1,0,1]
	v_lshlrev_b32_e32 v80, 16, v81
	v_pk_fma_f32 v[82:83], v[56:57], v[80:81], v[82:83] op_sel_hi:[1,0,1]
	v_pk_fma_f32 v[78:79], v[54:55], v[80:81], v[78:79] op_sel_hi:[1,0,1]
	v_bfi_b32 v80, v91, 0, v85
	v_pk_fma_f32 v[82:83], v[28:29], v[80:81], v[82:83] op_sel_hi:[1,0,1]
	v_pk_fma_f32 v[78:79], v[26:27], v[80:81], v[78:79] op_sel_hi:[1,0,1]
	v_bfi_b32 v80, v91, 0, v81
	v_pk_fma_f32 v[82:83], v[60:61], v[80:81], v[82:83] op_sel_hi:[1,0,1]
	v_pk_fma_f32 v[78:79], v[58:59], v[80:81], v[78:79] op_sel_hi:[1,0,1]
	v_min_f32_e32 v84, 0, v82
	v_min_f32_e32 v80, 0, v78
	v_mul_f32_e64 v78, |v78|, s21
	v_min_f32_e32 v81, 0, v79
	v_mul_f32_e64 v79, |v79|, s21
	v_mul_f32_e64 v82, |v82|, s21
	v_min_f32_e32 v85, 0, v83
	v_mul_f32_e64 v83, |v83|, s21
	v_exp_f32_e32 v78, v78
	v_exp_f32_e32 v79, v79
	v_exp_f32_e32 v82, v82
	v_exp_f32_e32 v83, v83
	v_add_f32_e32 v78, 1.0, v78
	v_add_f32_e32 v79, 1.0, v79
	v_add_f32_e32 v82, 1.0, v82
	v_add_f32_e32 v83, 1.0, v83
	v_log_f32_e32 v78, v78
	v_log_f32_e32 v79, v79
	v_log_f32_e32 v82, v82
	v_log_f32_e32 v83, v83
	s_lshl_b64 s[10:11], s[4:5], 10
	v_pk_fma_f32 v[78:79], v[78:79], s[16:17], v[80:81] op_sel_hi:[1,0,1]
	v_pk_fma_f32 v[82:83], v[82:83], s[16:17], v[84:85] op_sel_hi:[1,0,1]
	s_nop 0
	v_pk_mul_f32 v[80:81], v[82:83], s[20:21] op_sel_hi:[1,0]
	v_pk_mul_f32 v[78:79], v[78:79], s[20:21] op_sel_hi:[1,0]
	v_lshl_add_u64 v[82:83], v[100:101], 0, s[10:11]
	global_store_dwordx4 v[82:83], v[78:81], off
	v_and_b32_e32 v83, 0xffff0000, v75
	v_lshlrev_b32_e32 v82, 16, v75
	v_and_b32_e32 v79, 0xffff0000, v70
	v_lshlrev_b32_e32 v78, 16, v70
	v_mul_f32_e32 v70, v79, v79
	v_and_b32_e32 v81, 0xffff0000, v74
	v_lshlrev_b32_e32 v80, 16, v74
	v_pk_fma_f32 v[84:85], v[78:79], v[78:79], v[70:71] op_sel_hi:[1,1,0]
	v_and_b32_e32 v75, 0xffff0000, v71
	v_lshlrev_b32_e32 v74, 16, v71
	v_pk_fma_f32 v[70:71], v[74:75], v[74:75], v[84:85]
	v_mul_f32_e32 v84, v75, v75
	v_pk_add_f32 v[120:121], v[84:85], v[70:71] op_sel_hi:[0,1]
	v_and_b32_e32 v71, 0xffff0000, v72
	v_lshlrev_b32_e32 v70, 16, v72
	v_pk_mul_f32 v[124:125], v[80:81], v[80:81]
	v_pk_fma_f32 v[120:121], v[70:71], v[70:71], v[120:121]
	v_mul_f32_e32 v72, v71, v71
	v_pk_mul_f32 v[126:127], v[82:83], v[82:83]
	v_pk_add_f32 v[130:131], v[72:73], v[120:121] op_sel_hi:[0,1]
	v_add_f32_e32 v72, v124, v125
	v_and_b32_e32 v85, 0xffff0000, v76
	v_lshlrev_b32_e32 v84, 16, v76
	v_add_f32_e32 v72, v126, v72
	v_pk_mul_f32 v[128:129], v[84:85], v[84:85]
	v_add_f32_e32 v72, v127, v72
	v_and_b32_e32 v121, 0xffff0000, v77
	v_lshlrev_b32_e32 v120, 16, v77
	v_add_f32_e32 v72, v128, v72
	v_pk_mul_f32 v[132:133], v[120:121], v[120:121]
	v_add_f32_e32 v72, v129, v72
	v_and_b32_e32 v77, 0xffff0000, v73
	v_lshlrev_b32_e32 v76, 16, v73
	v_add_f32_e32 v72, v132, v72
	v_add_f32_e32 v123, v133, v72
	v_pk_fma_f32 v[72:73], v[76:77], v[76:77], v[130:131]
	v_mul_f32_e32 v124, v77, v77
	v_pk_add_f32 v[72:73], v[124:125], v[72:73] op_sel_hi:[0,1]
	v_mov_b32_e32 v73, v72
	v_mul_f32_e32 v72, v88, v88
	v_xor_b32_e32 v124, 16, v122
	v_lshlrev_b32_e32 v124, 2, v124
	v_add_f32_dpp v123, v123, v123 quad_perm:[1,0,3,2] row_mask:0xf bank_mask:0xf
	v_add_f32_dpp v72, v72, v72 quad_perm:[1,0,3,2] row_mask:0xf bank_mask:0xf
	v_add_f32_dpp v73, v73, v73 quad_perm:[1,0,3,2] row_mask:0xf bank_mask:0xf
	v_add_f32_dpp v123, v123, v123 quad_perm:[2,3,0,1] row_mask:0xf bank_mask:0xf
	v_add_f32_dpp v72, v72, v72 quad_perm:[2,3,0,1] row_mask:0xf bank_mask:0xf
	v_add_f32_dpp v73, v73, v73 quad_perm:[2,3,0,1] row_mask:0xf bank_mask:0xf
	v_add_f32_dpp v123, v123, v123 row_half_mirror row_mask:0xf bank_mask:0xf
	v_add_f32_dpp v72, v72, v72 row_half_mirror row_mask:0xf bank_mask:0xf
	v_add_f32_dpp v73, v73, v73 row_half_mirror row_mask:0xf bank_mask:0xf
	v_add_f32_dpp v123, v123, v123 row_mirror row_mask:0xf bank_mask:0xf
	v_add_f32_dpp v72, v72, v72 row_mirror row_mask:0xf bank_mask:0xf
	v_add_f32_dpp v73, v73, v73 row_mirror row_mask:0xf bank_mask:0xf
	v_mov_b32_e32 v125, v123
	v_mov_b32_e32 v126, v72
	v_mov_b32_e32 v127, v73
	v_permlane16_swap_b32_e32 v123, v125
	v_permlane16_swap_b32_e32 v72, v126
	v_permlane16_swap_b32_e32 v73, v127
	v_add_f32_e32 v123, v123, v125
	v_add_f32_e32 v72, v72, v126
	v_add_f32_e32 v73, v73, v127
	v_mov_b32_e32 v125, v123
	v_mov_b32_e32 v126, v72
	v_mov_b32_e32 v127, v73
	v_permlane32_swap_b32_e32 v123, v125
	v_permlane32_swap_b32_e32 v72, v126
	v_permlane32_swap_b32_e32 v73, v127
	v_add_f32_e32 v123, v123, v125
	v_add_f32_e32 v72, v72, v126
	v_add_f32_e32 v73, v73, v127
	v_mov_b32_e32 v125, v123
	v_mov_b32_e32 v126, 0
	v_mov_b32_e32 v122, 0
	v_mov_b32_e32 v123, 0
	s_and_saveexec_b64 s[12:13], s[0:1]
	s_cbranch_execz .LBB0_498
	v_add_f32_e32 v125, v125, v126
	v_fmamk_f32 v125, v125, 0x3b2aaaab, v118
	v_mul_f32_e32 v126, 0x4b800000, v125
	v_cmp_gt_f32_e32 vcc, s17, v125
	s_nop 1
	v_cndmask_b32_e32 v125, v125, v126, vcc
	v_rsq_f32_e32 v125, v125
	s_nop 0
	v_mul_f32_e32 v126, 0x45800000, v125
	v_cndmask_b32_e32 v126, v125, v126, vcc
	v_pk_mul_f32 v[80:81], v[126:127], v[80:81] op_sel_hi:[0,1]
	v_pk_mul_f32 v[82:83], v[126:127], v[82:83] op_sel_hi:[0,1]
	v_pk_mul_f32 v[84:85], v[126:127], v[84:85] op_sel_hi:[0,1]
	v_pk_mul_f32 v[120:121], v[126:127], v[120:121] op_sel_hi:[0,1]
	v_pk_mul_f32 v[80:81], v[80:81], v[136:137]
	v_pk_mul_f32 v[82:83], v[82:83], v[138:139]
	v_pk_mul_f32 v[84:85], v[84:85], v[140:141]
	v_pk_mul_f32 v[120:121], v[120:121], v[142:143]
	v_cvt_pk_bf16_f32 v80, v80, v81
	v_cvt_pk_bf16_f32 v81, v82, v83
	v_cvt_pk_bf16_f32 v82, v84, v85
	v_cvt_pk_bf16_f32 v83, v120, v121
	v_mad_i64_i32 v[84:85], s[10:11], s4, v119, v[102:103]
	global_store_dwordx4 v[84:85], v[80:83], off
